# P5 selected branch: block-selection mask applied as -inf MFMA SrcC bias before exp (four v_cndmask off the exp->PV chain); OC row pointers recomputed at the final epilogue to free the registers
# speedup vs baseline: 1.0056x; 1.0056x over previous
.LBB0_638:
	s_mov_b64 s[2:3], 0x2000
	v_lshl_add_u64 v[192:193], v[202:203], 0, s[2:3]
	s_mov_b64 s[2:3], 0x4000
	v_lshl_add_u64 v[194:195], v[202:203], 0, s[2:3]
	s_mov_b64 s[2:3], 0x6000
	v_lshl_add_u64 v[190:191], v[202:203], 0, s[2:3]
	global_load_dword v104, v[210:211], off offset:36
	global_load_dwordx4 v[106:109], v[202:203], off
	global_load_dwordx4 v[110:113], v[202:203], off offset:64
	global_load_dwordx4 v[114:117], v[202:203], off offset:128
	global_load_dwordx4 v[118:121], v[202:203], off offset:192
	global_load_dword v105, v[212:213], off offset:36
	global_load_dwordx4 v[122:125], v[192:193], off
	global_load_dwordx4 v[130:133], v[192:193], off offset:64
	global_load_dwordx4 v[134:137], v[192:193], off offset:128
	global_load_dwordx4 v[158:161], v[192:193], off offset:192
	global_load_dword v126, v[196:197], off offset:36
	global_load_dwordx4 v[162:165], v[194:195], off
	global_load_dwordx4 v[166:169], v[194:195], off offset:64
	global_load_dwordx4 v[170:173], v[194:195], off offset:128
	global_load_dwordx4 v[174:177], v[194:195], off offset:192
	global_load_dword v127, v[200:201], off offset:36
	global_load_dwordx4 v[178:181], v[190:191], off
	global_load_dwordx4 v[182:185], v[190:191], off offset:64
	global_load_dwordx4 v[186:189], v[190:191], off offset:128
	global_load_dwordx4 v[248:251], v[190:191], off offset:192
	v_add_f32_e32 v0, 0, v154
	v_add_f32_e32 v4, 0, v150
	v_add_f32_e32 v5, 0, v142
	v_add_f32_e32 v6, 0, v146
	s_mov_b64 s[40:41], 0
	s_waitcnt vmcnt(19)
	v_mul_f32_e32 v1, 0xbfb8aa3b, v104
	v_exp_f32_e32 v1, v1
	s_nop 0
	v_add_f32_e32 v1, 1.0, v1
	v_rcp_f32_e32 v1, v1
	s_nop 0
	v_div_scale_f32 v2, s[2:3], v0, v0, v1
	v_rcp_f32_e32 v3, v2
	s_nop 0
	v_fma_f32 v7, -v2, v3, 1.0
	v_fmac_f32_e32 v3, v7, v3
	v_div_scale_f32 v7, vcc, v1, v0, v1
	v_mul_f32_e32 v56, v7, v3
	v_fma_f32 v57, -v2, v56, v7
	v_fmac_f32_e32 v56, v57, v3
	v_fma_f32 v2, -v2, v56, v7
	v_div_fmas_f32 v2, v2, v3, v56
	v_div_fixup_f32 v2, v2, v0, v1
	v_lshl_add_u64 v[0:1], s[36:37], 0, v[214:215]
	v_lshl_add_u64 v[56:57], v[0:1], 0, v[128:129]
	v_lshlrev_b32_e32 v0, 1, v241
	v_mov_b32_e32 v1, v129
	v_lshl_add_u64 v[68:69], v[56:57], 0, v[0:1]
	s_waitcnt vmcnt(18)
	v_pk_fma_f32 v[56:57], v[100:101], v[2:3], v[106:107] op_sel_hi:[1,0,1]
	v_pk_fma_f32 v[58:59], v[102:103], v[2:3], v[108:109] op_sel_hi:[1,0,1]
	v_cvt_pk_bf16_f32 v56, v56, v57
	v_cvt_pk_bf16_f32 v57, v58, v59
	global_store_dwordx2 v[68:69], v[56:57], off offset:512
	s_waitcnt vmcnt(18)
	v_pk_fma_f32 v[56:57], v[72:73], v[2:3], v[110:111] op_sel_hi:[1,0,1]
	v_pk_fma_f32 v[58:59], v[74:75], v[2:3], v[112:113] op_sel_hi:[1,0,1]
	v_cvt_pk_bf16_f32 v56, v56, v57
	v_cvt_pk_bf16_f32 v57, v58, v59
	global_store_dwordx2 v[68:69], v[56:57], off offset:544
	s_waitcnt vmcnt(18)
	v_pk_fma_f32 v[56:57], v[64:65], v[2:3], v[114:115] op_sel_hi:[1,0,1]
	v_pk_fma_f32 v[58:59], v[66:67], v[2:3], v[116:117] op_sel_hi:[1,0,1]
	v_cvt_pk_bf16_f32 v56, v56, v57
	v_cvt_pk_bf16_f32 v57, v58, v59
	global_store_dwordx2 v[68:69], v[56:57], off offset:576
	s_waitcnt vmcnt(18)
	v_pk_fma_f32 v[56:57], v[60:61], v[2:3], v[118:119] op_sel_hi:[1,0,1]
	v_pk_fma_f32 v[2:3], v[62:63], v[2:3], v[120:121] op_sel_hi:[1,0,1]
	v_cvt_pk_bf16_f32 v56, v56, v57
	v_cvt_pk_bf16_f32 v57, v2, v3
	global_store_dwordx2 v[68:69], v[56:57], off offset:608
	s_waitcnt vmcnt(18)
	v_mul_f32_e32 v2, 0xbfb8aa3b, v105
	v_exp_f32_e32 v2, v2
	s_nop 0
	v_add_f32_e32 v2, 1.0, v2
	v_rcp_f32_e32 v2, v2
	s_nop 0
	v_div_scale_f32 v3, s[2:3], v4, v4, v2
	v_rcp_f32_e32 v7, v3
	s_nop 0
	v_fma_f32 v56, -v3, v7, 1.0
	v_fmac_f32_e32 v7, v56, v7
	v_div_scale_f32 v56, vcc, v2, v4, v2
	v_mul_f32_e32 v57, v56, v7
	v_fma_f32 v58, -v3, v57, v56
	v_fmac_f32_e32 v57, v58, v7
	v_fma_f32 v3, -v3, v57, v56
	v_div_fmas_f32 v3, v3, v7, v57
	v_div_fixup_f32 v4, v3, v4, v2
	v_lshl_add_u64 v[2:3], s[36:37], 0, v[216:217]
	v_lshl_add_u64 v[2:3], v[2:3], 0, v[128:129]
	v_lshl_add_u64 v[2:3], v[2:3], 0, v[0:1]
	s_waitcnt vmcnt(17)
	v_pk_fma_f32 v[52:53], v[52:53], v[4:5], v[122:123] op_sel_hi:[1,0,1]
	v_pk_fma_f32 v[54:55], v[54:55], v[4:5], v[124:125] op_sel_hi:[1,0,1]
	v_cvt_pk_bf16_f32 v52, v52, v53
	v_cvt_pk_bf16_f32 v53, v54, v55
	global_store_dwordx2 v[2:3], v[52:53], off offset:512
	s_waitcnt vmcnt(17)
	v_pk_fma_f32 v[48:49], v[48:49], v[4:5], v[130:131] op_sel_hi:[1,0,1]
	v_pk_fma_f32 v[50:51], v[50:51], v[4:5], v[132:133] op_sel_hi:[1,0,1]
	v_cvt_pk_bf16_f32 v48, v48, v49
	v_cvt_pk_bf16_f32 v49, v50, v51
	global_store_dwordx2 v[2:3], v[48:49], off offset:544
	s_waitcnt vmcnt(17)
	v_pk_fma_f32 v[44:45], v[44:45], v[4:5], v[134:135] op_sel_hi:[1,0,1]
	v_pk_fma_f32 v[46:47], v[46:47], v[4:5], v[136:137] op_sel_hi:[1,0,1]
	v_cvt_pk_bf16_f32 v44, v44, v45
	v_cvt_pk_bf16_f32 v45, v46, v47
	global_store_dwordx2 v[2:3], v[44:45], off offset:576
	s_waitcnt vmcnt(17)
	v_pk_fma_f32 v[40:41], v[40:41], v[4:5], v[158:159] op_sel_hi:[1,0,1]
	v_pk_fma_f32 v[42:43], v[42:43], v[4:5], v[160:161] op_sel_hi:[1,0,1]
	v_cvt_pk_bf16_f32 v40, v40, v41
	v_cvt_pk_bf16_f32 v41, v42, v43
	global_store_dwordx2 v[2:3], v[40:41], off offset:608
	s_waitcnt vmcnt(17)
	v_mul_f32_e32 v2, 0xbfb8aa3b, v126
	v_exp_f32_e32 v2, v2
	s_nop 0
	v_add_f32_e32 v2, 1.0, v2
	v_rcp_f32_e32 v2, v2
	s_nop 0
	v_div_scale_f32 v3, s[2:3], v6, v6, v2
	v_rcp_f32_e32 v4, v3
	s_nop 0
	v_fma_f32 v7, -v3, v4, 1.0
	v_fmac_f32_e32 v4, v7, v4
	v_div_scale_f32 v7, vcc, v2, v6, v2
	v_mul_f32_e32 v40, v7, v4
	v_fma_f32 v41, -v3, v40, v7
	v_fmac_f32_e32 v40, v41, v4
	v_fma_f32 v3, -v3, v40, v7
	v_div_fmas_f32 v3, v3, v4, v40
	v_div_fixup_f32 v2, v3, v6, v2
	v_lshl_add_u64 v[6:7], s[36:37], 0, v[204:205]
	v_lshl_add_u64 v[6:7], v[6:7], 0, v[128:129]
	v_lshl_add_u64 v[6:7], v[6:7], 0, v[0:1]
	s_waitcnt vmcnt(16)
	v_pk_fma_f32 v[36:37], v[36:37], v[2:3], v[162:163] op_sel_hi:[1,0,1]
	v_pk_fma_f32 v[38:39], v[38:39], v[2:3], v[164:165] op_sel_hi:[1,0,1]
	v_cvt_pk_bf16_f32 v36, v36, v37
	v_cvt_pk_bf16_f32 v37, v38, v39
	global_store_dwordx2 v[6:7], v[36:37], off offset:512
	s_waitcnt vmcnt(16)
	v_pk_fma_f32 v[32:33], v[32:33], v[2:3], v[166:167] op_sel_hi:[1,0,1]
	v_pk_fma_f32 v[34:35], v[34:35], v[2:3], v[168:169] op_sel_hi:[1,0,1]
	v_cvt_pk_bf16_f32 v32, v32, v33
	v_cvt_pk_bf16_f32 v33, v34, v35
	global_store_dwordx2 v[6:7], v[32:33], off offset:544
	s_waitcnt vmcnt(16)
	v_pk_fma_f32 v[28:29], v[28:29], v[2:3], v[170:171] op_sel_hi:[1,0,1]
	v_pk_fma_f32 v[30:31], v[30:31], v[2:3], v[172:173] op_sel_hi:[1,0,1]
	v_cvt_pk_bf16_f32 v28, v28, v29
	v_cvt_pk_bf16_f32 v29, v30, v31
	global_store_dwordx2 v[6:7], v[28:29], off offset:576
	s_waitcnt vmcnt(16)
	v_pk_fma_f32 v[24:25], v[24:25], v[2:3], v[174:175] op_sel_hi:[1,0,1]
	v_pk_fma_f32 v[2:3], v[26:27], v[2:3], v[176:177] op_sel_hi:[1,0,1]
	v_cvt_pk_bf16_f32 v24, v24, v25
	v_cvt_pk_bf16_f32 v25, v2, v3
	global_store_dwordx2 v[6:7], v[24:25], off offset:608
	s_waitcnt vmcnt(16)
	v_mul_f32_e32 v2, 0xbfb8aa3b, v127
	v_exp_f32_e32 v2, v2
	s_nop 0
	v_add_f32_e32 v2, 1.0, v2
	v_rcp_f32_e32 v2, v2
	s_nop 0
	v_div_scale_f32 v3, s[2:3], v5, v5, v2
	v_rcp_f32_e32 v4, v3
	s_nop 0
	v_fma_f32 v6, -v3, v4, 1.0
	v_fmac_f32_e32 v4, v6, v4
	v_div_scale_f32 v6, vcc, v2, v5, v2
	v_mul_f32_e32 v7, v6, v4
	v_fma_f32 v24, -v3, v7, v6
	v_fmac_f32_e32 v7, v24, v4
	v_fma_f32 v3, -v3, v7, v6
	v_div_fmas_f32 v3, v3, v4, v7
	v_div_fixup_f32 v2, v3, v5, v2
	v_lshl_add_u64 v[4:5], s[36:37], 0, v[206:207]
	v_lshl_add_u64 v[4:5], v[4:5], 0, v[128:129]
	v_lshl_add_u64 v[0:1], v[4:5], 0, v[0:1]
	s_waitcnt vmcnt(15)
	v_pk_fma_f32 v[4:5], v[20:21], v[2:3], v[178:179] op_sel_hi:[1,0,1]
	v_pk_fma_f32 v[6:7], v[22:23], v[2:3], v[180:181] op_sel_hi:[1,0,1]
	v_cvt_pk_bf16_f32 v4, v4, v5
	v_cvt_pk_bf16_f32 v5, v6, v7
	global_store_dwordx2 v[0:1], v[4:5], off offset:512
	s_waitcnt vmcnt(15)
	v_pk_fma_f32 v[4:5], v[16:17], v[2:3], v[182:183] op_sel_hi:[1,0,1]
	v_pk_fma_f32 v[6:7], v[18:19], v[2:3], v[184:185] op_sel_hi:[1,0,1]
	v_cvt_pk_bf16_f32 v4, v4, v5
	v_cvt_pk_bf16_f32 v5, v6, v7
	global_store_dwordx2 v[0:1], v[4:5], off offset:544
	s_waitcnt vmcnt(15)
	v_pk_fma_f32 v[4:5], v[12:13], v[2:3], v[186:187] op_sel_hi:[1,0,1]
	v_pk_fma_f32 v[6:7], v[14:15], v[2:3], v[188:189] op_sel_hi:[1,0,1]
	v_cvt_pk_bf16_f32 v4, v4, v5
	v_cvt_pk_bf16_f32 v5, v6, v7
	global_store_dwordx2 v[0:1], v[4:5], off offset:576
	s_waitcnt vmcnt(15)
	v_pk_fma_f32 v[4:5], v[8:9], v[2:3], v[248:249] op_sel_hi:[1,0,1]
	v_pk_fma_f32 v[2:3], v[10:11], v[2:3], v[250:251] op_sel_hi:[1,0,1]
	v_cvt_pk_bf16_f32 v4, v4, v5
	v_cvt_pk_bf16_f32 v5, v2, v3
	global_store_dwordx2 v[0:1], v[4:5], off offset:608

.LBB0_752:
	v_and_b32_e32 v5, 12, v8
	v_lshrrev_b32_e32 v2, 4, v8
	v_lshrrev_b32_e64 v5, v5, s2
	v_xor_b32_e32 v2, v5, v2
	v_lshlrev_b32_e32 v3, 6, v7
	v_lshlrev_b32_e32 v2, 4, v2
	v_and_or_b32 v244, v2, 48, v3
	v_lshrrev_b32_e32 v2, 1, v7
	v_xor_b32_e32 v5, v2, v11
	v_bitop3_b32 v2, v11, v2, 4 bitop3:0x36
	v_lshlrev_b32_e32 v6, 4, v2
	v_lshlrev_b32_e32 v2, 3, v7
	v_lshlrev_b32_e32 v3, 5, v240
	v_and_b32_e32 v2, 0x60, v2
	s_mov_b32 s2, 0x11000
	v_add3_u32 v245, v3, v2, s2
	s_mov_b32 s45, s85
	v_and_b32_e32 v2, 3, v8
	v_lshl_add_u64 v[0:1], s[44:45], 0, v[0:1]
	v_lshlrev_b32_e32 v2, 4, v2
	v_mov_b32_e32 v3, v129
	v_lshlrev_b32_e32 v10, 2, v11
	v_lshl_add_u64 v[0:1], v[0:1], 0, v[2:3]
	s_waitcnt lgkmcnt(0)
	v_lshrrev_b32_e32 v9, 2, v7
	v_lshl_add_u64 v[198:199], s[62:63], 0, v[0:1]
	v_lshl_or_b32 v0, s64, 6, v10
	v_mov_b32_e32 v10, v129
	v_mov_b32_e32 v11, v129
	v_lshlrev_b32_e32 v4, 7, v7
	v_lshlrev_b32_e32 v5, 4, v5
	v_sub_u32_e32 v0, v0, v9
	v_mov_b32_e32 v8, v129
	v_mov_b32_e32 v9, v129
	v_mov_b64_e32 v[26:27], v[10:11]
	v_mov_b64_e32 v[42:43], v[10:11]
	s_waitcnt lgkmcnt(13)
	v_mov_b64_e32 v[62:63], v[10:11]
	v_mov_b64_e32 v[14:15], v[10:11]
	v_mov_b64_e32 v[30:31], v[10:11]
	v_mov_b64_e32 v[46:47], v[10:11]
	s_waitcnt lgkmcnt(12)
	v_mov_b64_e32 v[66:67], v[10:11]
	v_mov_b64_e32 v[18:19], v[10:11]
	v_mov_b64_e32 v[34:35], v[10:11]
	v_mov_b64_e32 v[50:51], v[10:11]
	v_mov_b64_e32 v[74:75], v[10:11]
	v_mov_b64_e32 v[22:23], v[10:11]
	v_mov_b64_e32 v[38:39], v[10:11]
	v_mov_b64_e32 v[54:55], v[10:11]
	v_mov_b64_e32 v[102:103], v[10:11]
	v_mov_b64_e32 v[144:145], v[10:11]
	v_mov_b64_e32 v[148:149], v[10:11]
	v_mov_b64_e32 v[152:153], v[10:11]
	v_mov_b64_e32 v[156:157], v[10:11]
	v_lshlrev_b32_e32 v241, 2, v241
	s_mov_b32 s27, 4
	v_mov_b32_e32 v139, v138
	v_mov_b32_e32 v140, v138
	v_mov_b32_e32 v141, v138
	v_sub_u32_e32 v240, v0, v240
	s_movk_i32 s28, 0x120
	v_add_u32_e32 v246, v4, v5
	v_add_u32_e32 v247, v4, v6
	v_mov_b64_e32 v[24:25], v[8:9]
	v_mov_b64_e32 v[40:41], v[8:9]
	v_mov_b64_e32 v[60:61], v[8:9]
	v_mov_b64_e32 v[12:13], v[8:9]
	v_mov_b64_e32 v[28:29], v[8:9]
	v_mov_b64_e32 v[44:45], v[8:9]
	v_mov_b64_e32 v[64:65], v[8:9]
	v_mov_b64_e32 v[16:17], v[8:9]
	v_mov_b64_e32 v[32:33], v[8:9]
	v_mov_b64_e32 v[48:49], v[8:9]
	v_mov_b64_e32 v[72:73], v[8:9]
	v_mov_b64_e32 v[20:21], v[8:9]
	v_mov_b64_e32 v[36:37], v[8:9]
	v_mov_b64_e32 v[52:53], v[8:9]
	v_mov_b64_e32 v[100:101], v[8:9]
	v_mov_b64_e32 v[142:143], v[8:9]
	v_mov_b64_e32 v[146:147], v[8:9]
	v_mov_b64_e32 v[150:151], v[8:9]
	v_mov_b64_e32 v[154:155], v[8:9]
	v_mov_b32_e32 v194, 0xff800000
	s_barrier
	s_branch .LBB0_756
.LBB0_753:
	v_cvt_pk_bf16_f32 v0, v0, v1
	v_cvt_pk_bf16_f32 v1, v2, v3
	v_cvt_pk_bf16_f32 v2, v4, v5
	v_cvt_pk_bf16_f32 v3, v6, v7
	s_waitcnt lgkmcnt(3)
	s_nop 0
	v_mfma_f32_16x16x32_bf16 v[20:23], v[158:161], v[0:3], v[20:23]
	s_waitcnt lgkmcnt(2)
	v_mfma_f32_16x16x32_bf16 v[16:19], v[162:165], v[0:3], v[16:19]
	s_waitcnt lgkmcnt(1)
	v_mfma_f32_16x16x32_bf16 v[12:15], v[166:169], v[0:3], v[12:15]
	s_waitcnt lgkmcnt(0)
	v_mfma_f32_16x16x32_bf16 v[8:11], v[170:173], v[0:3], v[8:11]
	v_mfma_f32_16x16x32_bf16 v[142:145], v[138:141], v[0:3], v[142:145]

.Lsel_have_words:
	v_and_b32_e32 v0, s70, v250
	v_cmp_ne_u32_e64 s[50:51], 0, v0
	v_and_b32_e32 v0, s70, v251
	v_cmp_ne_u32_e64 s[48:49], 0, v0
	v_and_b32_e32 v0, s70, v249
	v_cmp_ne_u32_e64 s[46:47], 0, v0
	v_and_b32_e32 v0, s70, v248
	v_cmp_ne_u32_e64 s[42:43], 0, v0
	s_mov_b64 s[86:87], s[50:51]
	s_mov_b64 s[88:89], s[48:49]
	s_mov_b64 s[90:91], s[46:47]
	s_mov_b64 s[92:93], s[42:43]
	s_or_b64 s[2:3], s[48:49], s[50:51]
	s_or_b64 s[2:3], s[2:3], s[46:47]
	s_or_b64 s[2:3], s[2:3], s[42:43]
	s_cmp_eq_u64 s[2:3], 0
	s_cbranch_scc1 .LBB0_785
	ds_read_b128 v[182:185], v246
	ds_read_b128 v[178:181], v246 offset:2048
	ds_read_b128 v[186:189], v247
	ds_read_b128 v[174:177], v247 offset:2048
	ds_read_b128 v[158:161], v244 offset:4096
	ds_read_b128 v[162:165], v244 offset:5120
	ds_read_b128 v[166:169], v244 offset:6144
	ds_read_b128 v[170:173], v244 offset:7168
	s_add_i32 s2, s28, 0xfffffeff
	s_cmp_le_i32 s2, s26
	s_cselect_b64 s[2:3], -1, 0
	v_cndmask_b32_e64 v0, 0, 1, s[2:3]
	s_cmp_eq_u64 s[50:51], 0
	v_cmp_ne_u32_e64 s[44:45], 1, v0
	s_cbranch_scc1 .LBB0_767
	v_cndmask_b32_e64 v190, v194, 0, s[50:51]
	v_cndmask_b32_e64 v191, v194, 0, s[50:51]
	v_cndmask_b32_e64 v192, v194, 0, s[50:51]
	v_cndmask_b32_e64 v193, v194, 0, s[50:51]
	s_nop 0
	s_waitcnt lgkmcnt(7)
	v_mfma_f32_16x16x32_bf16 v[0:3], v[182:185], v[104:107], v[190:193]
	s_and_b64 vcc, exec, s[44:45]
	s_mov_b64 s[64:65], -1
	s_waitcnt lgkmcnt(6)
	v_mfma_f32_16x16x32_bf16 v[4:7], v[178:181], v[104:107], v[190:193]
	s_waitcnt lgkmcnt(5)
	v_mfma_f32_16x16x32_bf16 v[0:3], v[186:189], v[108:111], v[0:3]
	s_waitcnt lgkmcnt(4)
	v_mfma_f32_16x16x32_bf16 v[4:7], v[174:177], v[108:111], v[4:7]
	s_nop 5
	v_exp_f32_e32 v0, v0
	v_exp_f32_e32 v1, v1
	v_exp_f32_e32 v2, v2
	v_exp_f32_e32 v3, v3
	v_exp_f32_e32 v4, v4
	v_exp_f32_e32 v5, v5
	v_exp_f32_e32 v6, v6
	v_exp_f32_e32 v7, v7
	s_cbranch_vccz .LBB0_766

.LBB0_766:
	v_cvt_pk_bf16_f32 v0, v0, v1
	v_cvt_pk_bf16_f32 v1, v2, v3
	v_cvt_pk_bf16_f32 v2, v4, v5
	v_cvt_pk_bf16_f32 v3, v6, v7
	s_waitcnt lgkmcnt(3)
	s_nop 0
	v_mfma_f32_16x16x32_bf16 v[100:103], v[158:161], v[0:3], v[100:103]
	s_waitcnt lgkmcnt(2)
	v_mfma_f32_16x16x32_bf16 v[72:75], v[162:165], v[0:3], v[72:75]
	s_waitcnt lgkmcnt(1)
	v_mfma_f32_16x16x32_bf16 v[64:67], v[166:169], v[0:3], v[64:67]
	s_waitcnt lgkmcnt(0)
	v_mfma_f32_16x16x32_bf16 v[60:63], v[170:173], v[0:3], v[60:63]
	v_mfma_f32_16x16x32_bf16 v[154:157], v[138:141], v[0:3], v[154:157]
.LBB0_767:
	s_cmp_eq_u64 s[48:49], 0
	s_cbranch_scc1 .LBB0_773
	v_cndmask_b32_e64 v190, v194, 0, s[48:49]
	v_cndmask_b32_e64 v191, v194, 0, s[48:49]
	v_cndmask_b32_e64 v192, v194, 0, s[48:49]
	v_cndmask_b32_e64 v193, v194, 0, s[48:49]
	s_nop 0
	s_waitcnt lgkmcnt(7)
	v_mfma_f32_16x16x32_bf16 v[0:3], v[182:185], v[112:115], v[190:193]
	s_and_b64 vcc, exec, s[44:45]
	s_mov_b64 s[50:51], -1
	s_waitcnt lgkmcnt(6)
	v_mfma_f32_16x16x32_bf16 v[4:7], v[178:181], v[112:115], v[190:193]
	s_waitcnt lgkmcnt(5)
	v_mfma_f32_16x16x32_bf16 v[0:3], v[186:189], v[116:119], v[0:3]
	s_waitcnt lgkmcnt(4)
	v_mfma_f32_16x16x32_bf16 v[4:7], v[174:177], v[116:119], v[4:7]
	s_nop 5
	v_exp_f32_e32 v0, v0
	v_exp_f32_e32 v1, v1
	v_exp_f32_e32 v2, v2
	v_exp_f32_e32 v3, v3
	v_exp_f32_e32 v4, v4
	v_exp_f32_e32 v5, v5
	v_exp_f32_e32 v6, v6
	v_exp_f32_e32 v7, v7
	s_cbranch_vccz .LBB0_772

.LBB0_772:
	v_cvt_pk_bf16_f32 v0, v0, v1
	v_cvt_pk_bf16_f32 v1, v2, v3
	v_cvt_pk_bf16_f32 v2, v4, v5
	v_cvt_pk_bf16_f32 v3, v6, v7
	s_waitcnt lgkmcnt(3)
	s_nop 0
	v_mfma_f32_16x16x32_bf16 v[52:55], v[158:161], v[0:3], v[52:55]
	s_waitcnt lgkmcnt(2)
	v_mfma_f32_16x16x32_bf16 v[48:51], v[162:165], v[0:3], v[48:51]
	s_waitcnt lgkmcnt(1)
	v_mfma_f32_16x16x32_bf16 v[44:47], v[166:169], v[0:3], v[44:47]
	s_waitcnt lgkmcnt(0)
	v_mfma_f32_16x16x32_bf16 v[40:43], v[170:173], v[0:3], v[40:43]
	v_mfma_f32_16x16x32_bf16 v[150:153], v[138:141], v[0:3], v[150:153]
.LBB0_773:
	s_cmp_eq_u64 s[46:47], 0
	s_cbranch_scc1 .LBB0_779
	v_cndmask_b32_e64 v190, v194, 0, s[46:47]
	v_cndmask_b32_e64 v191, v194, 0, s[46:47]
	v_cndmask_b32_e64 v192, v194, 0, s[46:47]
	v_cndmask_b32_e64 v193, v194, 0, s[46:47]
	s_nop 0
	s_waitcnt lgkmcnt(7)
	v_mfma_f32_16x16x32_bf16 v[0:3], v[182:185], v[120:123], v[190:193]
	s_and_b64 vcc, exec, s[44:45]
	s_mov_b64 s[48:49], -1
	s_waitcnt lgkmcnt(6)
	v_mfma_f32_16x16x32_bf16 v[4:7], v[178:181], v[120:123], v[190:193]
	s_waitcnt lgkmcnt(5)
	v_mfma_f32_16x16x32_bf16 v[0:3], v[186:189], v[124:127], v[0:3]
	s_waitcnt lgkmcnt(4)
	v_mfma_f32_16x16x32_bf16 v[4:7], v[174:177], v[124:127], v[4:7]
	s_nop 5
	v_exp_f32_e32 v0, v0
	v_exp_f32_e32 v1, v1
	v_exp_f32_e32 v2, v2
	v_exp_f32_e32 v3, v3
	v_exp_f32_e32 v4, v4
	v_exp_f32_e32 v5, v5
	v_exp_f32_e32 v6, v6
	v_exp_f32_e32 v7, v7
	s_cbranch_vccz .LBB0_778

.LBB0_778:
	v_cvt_pk_bf16_f32 v0, v0, v1
	v_cvt_pk_bf16_f32 v1, v2, v3
	v_cvt_pk_bf16_f32 v2, v4, v5
	v_cvt_pk_bf16_f32 v3, v6, v7
	s_waitcnt lgkmcnt(3)
	s_nop 0
	v_mfma_f32_16x16x32_bf16 v[36:39], v[158:161], v[0:3], v[36:39]
	s_waitcnt lgkmcnt(2)
	v_mfma_f32_16x16x32_bf16 v[32:35], v[162:165], v[0:3], v[32:35]
	s_waitcnt lgkmcnt(1)
	v_mfma_f32_16x16x32_bf16 v[28:31], v[166:169], v[0:3], v[28:31]
	s_waitcnt lgkmcnt(0)
	v_mfma_f32_16x16x32_bf16 v[24:27], v[170:173], v[0:3], v[24:27]
	v_mfma_f32_16x16x32_bf16 v[146:149], v[138:141], v[0:3], v[146:149]
.LBB0_779:
	s_cmp_eq_u64 s[42:43], 0
	s_cbranch_scc1 .LBB0_785
	v_cndmask_b32_e64 v190, v194, 0, s[42:43]
	v_cndmask_b32_e64 v191, v194, 0, s[42:43]
	v_cndmask_b32_e64 v192, v194, 0, s[42:43]
	v_cndmask_b32_e64 v193, v194, 0, s[42:43]
	s_nop 0
	s_waitcnt lgkmcnt(7)
	v_mfma_f32_16x16x32_bf16 v[0:3], v[182:185], v[130:133], v[190:193]
	s_and_b64 vcc, exec, s[44:45]
	s_mov_b64 s[44:45], -1
	s_waitcnt lgkmcnt(6)
	v_mfma_f32_16x16x32_bf16 v[4:7], v[178:181], v[130:133], v[190:193]
	s_waitcnt lgkmcnt(5)
	v_mfma_f32_16x16x32_bf16 v[0:3], v[186:189], v[134:137], v[0:3]
	s_waitcnt lgkmcnt(4)
	v_mfma_f32_16x16x32_bf16 v[4:7], v[174:177], v[134:137], v[4:7]
	s_nop 5
	v_exp_f32_e32 v0, v0
	v_exp_f32_e32 v1, v1
	v_exp_f32_e32 v2, v2
	v_exp_f32_e32 v3, v3
	v_exp_f32_e32 v4, v4
	v_exp_f32_e32 v5, v5
	v_exp_f32_e32 v6, v6
	v_exp_f32_e32 v7, v7
	s_cbranch_vccz .LBB0_784

.LBB0_785:
	s_mov_b64 s[50:51], s[86:87]
	s_mov_b64 s[48:49], s[88:89]
	s_mov_b64 s[46:47], s[90:91]
	s_mov_b64 s[42:43], s[92:93]
	s_or_b64 s[2:3], s[48:49], s[50:51]
	s_or_b64 s[2:3], s[2:3], s[46:47]
	s_or_b64 s[2:3], s[2:3], s[42:43]
	s_cmp_eq_u64 s[2:3], 0
	s_cbranch_scc1 .LBB0_810
	ds_read_b128 v[182:185], v246 offset:8192
	ds_read_b128 v[178:181], v246 offset:10240
	ds_read_b128 v[186:189], v247 offset:8192
	ds_read_b128 v[174:177], v247 offset:10240
	ds_read_b128 v[158:161], v244 offset:12288
	ds_read_b128 v[162:165], v244 offset:13312
	ds_read_b128 v[166:169], v244 offset:14336
	ds_read_b128 v[170:173], v244 offset:15360
	s_add_i32 s2, s28, 0xffffff1f
	s_cmp_le_i32 s2, s26
	s_cselect_b64 s[2:3], -1, 0
	v_cndmask_b32_e64 v0, 0, 1, s[2:3]
	s_cmp_eq_u64 s[50:51], 0
	v_cmp_ne_u32_e64 s[44:45], 1, v0
	s_cbranch_scc1 .LBB0_792
	v_cndmask_b32_e64 v190, v194, 0, s[50:51]
	v_cndmask_b32_e64 v191, v194, 0, s[50:51]
	v_cndmask_b32_e64 v192, v194, 0, s[50:51]
	v_cndmask_b32_e64 v193, v194, 0, s[50:51]
	s_nop 0
	s_waitcnt lgkmcnt(7)
	v_mfma_f32_16x16x32_bf16 v[0:3], v[182:185], v[104:107], v[190:193]
	s_and_b64 vcc, exec, s[44:45]
	s_mov_b64 s[64:65], -1
	s_waitcnt lgkmcnt(6)
	v_mfma_f32_16x16x32_bf16 v[4:7], v[178:181], v[104:107], v[190:193]
	s_waitcnt lgkmcnt(5)
	v_mfma_f32_16x16x32_bf16 v[0:3], v[186:189], v[108:111], v[0:3]
	s_waitcnt lgkmcnt(4)
	v_mfma_f32_16x16x32_bf16 v[4:7], v[174:177], v[108:111], v[4:7]
	s_nop 5
	v_exp_f32_e32 v0, v0
	v_exp_f32_e32 v1, v1
	v_exp_f32_e32 v2, v2
	v_exp_f32_e32 v3, v3
	v_exp_f32_e32 v4, v4
	v_exp_f32_e32 v5, v5
	v_exp_f32_e32 v6, v6
	v_exp_f32_e32 v7, v7
	s_cbranch_vccz .LBB0_791

.LBB0_815:
	s_add_i32 s2, s27, -3
	s_lshl_b32 s64, 1, s2
	v_and_b32_e32 v0, s64, v250
	v_cmp_ne_u32_e64 s[50:51], 0, v0
	v_and_b32_e32 v0, s64, v251
	v_cmp_ne_u32_e64 s[48:49], 0, v0
	v_and_b32_e32 v0, s64, v249
	v_cmp_ne_u32_e64 s[46:47], 0, v0
	v_and_b32_e32 v0, s64, v248
	v_cmp_ne_u32_e64 s[42:43], 0, v0
	s_mov_b64 s[86:87], s[50:51]
	s_mov_b64 s[88:89], s[48:49]
	s_mov_b64 s[90:91], s[46:47]
	s_mov_b64 s[92:93], s[42:43]
	s_or_b64 s[2:3], s[48:49], s[50:51]
	s_or_b64 s[2:3], s[2:3], s[46:47]
	s_or_b64 s[2:3], s[2:3], s[42:43]
	s_cmp_eq_u64 s[2:3], 0
	s_cbranch_scc1 .LBB0_840
	ds_read_b128 v[182:185], v246 offset:16384
	ds_read_b128 v[178:181], v246 offset:18432
	ds_read_b128 v[186:189], v247 offset:16384
	ds_read_b128 v[174:177], v247 offset:18432
	ds_read_b128 v[158:161], v244 offset:20480
	ds_read_b128 v[162:165], v244 offset:21504
	ds_read_b128 v[166:169], v244 offset:22528
	ds_read_b128 v[170:173], v244 offset:23552
	s_add_i32 s2, s28, 0xffffff3f
	s_cmp_le_i32 s2, s26
	s_cselect_b64 s[2:3], -1, 0
	v_cndmask_b32_e64 v0, 0, 1, s[2:3]
	s_cmp_eq_u64 s[50:51], 0
	v_cmp_ne_u32_e64 s[44:45], 1, v0
	s_cbranch_scc1 .LBB0_822
	v_cndmask_b32_e64 v190, v194, 0, s[50:51]
	v_cndmask_b32_e64 v191, v194, 0, s[50:51]
	v_cndmask_b32_e64 v192, v194, 0, s[50:51]
	v_cndmask_b32_e64 v193, v194, 0, s[50:51]
	s_nop 0
	s_waitcnt lgkmcnt(7)
	v_mfma_f32_16x16x32_bf16 v[0:3], v[182:185], v[104:107], v[190:193]
	s_and_b64 vcc, exec, s[44:45]
	s_mov_b64 s[40:41], -1
	s_waitcnt lgkmcnt(6)
	v_mfma_f32_16x16x32_bf16 v[4:7], v[178:181], v[104:107], v[190:193]
	s_waitcnt lgkmcnt(5)
	v_mfma_f32_16x16x32_bf16 v[0:3], v[186:189], v[108:111], v[0:3]
	s_waitcnt lgkmcnt(4)
	v_mfma_f32_16x16x32_bf16 v[4:7], v[174:177], v[108:111], v[4:7]
	s_nop 5
	v_exp_f32_e32 v0, v0
	v_exp_f32_e32 v1, v1
	v_exp_f32_e32 v2, v2
	v_exp_f32_e32 v3, v3
	v_exp_f32_e32 v4, v4
	v_exp_f32_e32 v5, v5
	v_exp_f32_e32 v6, v6
	v_exp_f32_e32 v7, v7
	s_cbranch_vccz .LBB0_821

.LBB0_822:
	s_cmp_eq_u64 s[48:49], 0
	s_cbranch_scc1 .LBB0_828
	v_cndmask_b32_e64 v190, v194, 0, s[48:49]
	v_cndmask_b32_e64 v191, v194, 0, s[48:49]
	v_cndmask_b32_e64 v192, v194, 0, s[48:49]
	v_cndmask_b32_e64 v193, v194, 0, s[48:49]
	s_nop 0
	s_waitcnt lgkmcnt(7)
	v_mfma_f32_16x16x32_bf16 v[0:3], v[182:185], v[112:115], v[190:193]
	s_and_b64 vcc, exec, s[44:45]
	s_mov_b64 s[40:41], -1
	s_waitcnt lgkmcnt(6)
	v_mfma_f32_16x16x32_bf16 v[4:7], v[178:181], v[112:115], v[190:193]
	s_waitcnt lgkmcnt(5)
	v_mfma_f32_16x16x32_bf16 v[0:3], v[186:189], v[116:119], v[0:3]
	s_waitcnt lgkmcnt(4)
	v_mfma_f32_16x16x32_bf16 v[4:7], v[174:177], v[116:119], v[4:7]
	s_nop 5
	v_exp_f32_e32 v0, v0
	v_exp_f32_e32 v1, v1
	v_exp_f32_e32 v2, v2
	v_exp_f32_e32 v3, v3
	v_exp_f32_e32 v4, v4
	v_exp_f32_e32 v5, v5
	v_exp_f32_e32 v6, v6
	v_exp_f32_e32 v7, v7
	s_cbranch_vccz .LBB0_827

.LBB0_828:
	s_cmp_eq_u64 s[46:47], 0
	s_cbranch_scc1 .LBB0_834
	v_cndmask_b32_e64 v190, v194, 0, s[46:47]
	v_cndmask_b32_e64 v191, v194, 0, s[46:47]
	v_cndmask_b32_e64 v192, v194, 0, s[46:47]
	v_cndmask_b32_e64 v193, v194, 0, s[46:47]
	s_nop 0
	s_waitcnt lgkmcnt(7)
	v_mfma_f32_16x16x32_bf16 v[0:3], v[182:185], v[120:123], v[190:193]
	s_and_b64 vcc, exec, s[44:45]
	s_mov_b64 s[40:41], -1
	s_waitcnt lgkmcnt(6)
	v_mfma_f32_16x16x32_bf16 v[4:7], v[178:181], v[120:123], v[190:193]
	s_waitcnt lgkmcnt(5)
	v_mfma_f32_16x16x32_bf16 v[0:3], v[186:189], v[124:127], v[0:3]
	s_waitcnt lgkmcnt(4)
	v_mfma_f32_16x16x32_bf16 v[4:7], v[174:177], v[124:127], v[4:7]
	s_nop 5
	v_exp_f32_e32 v0, v0
	v_exp_f32_e32 v1, v1
	v_exp_f32_e32 v2, v2
	v_exp_f32_e32 v3, v3
	v_exp_f32_e32 v4, v4
	v_exp_f32_e32 v5, v5
	v_exp_f32_e32 v6, v6
	v_exp_f32_e32 v7, v7
	s_cbranch_vccz .LBB0_833

.LBB0_834:
	s_cmp_eq_u64 s[42:43], 0
	s_cbranch_scc1 .LBB0_840
	v_cndmask_b32_e64 v190, v194, 0, s[42:43]
	v_cndmask_b32_e64 v191, v194, 0, s[42:43]
	v_cndmask_b32_e64 v192, v194, 0, s[42:43]
	v_cndmask_b32_e64 v193, v194, 0, s[42:43]
	s_nop 0
	s_waitcnt lgkmcnt(7)
	v_mfma_f32_16x16x32_bf16 v[0:3], v[182:185], v[130:133], v[190:193]
	s_and_b64 vcc, exec, s[44:45]
	s_mov_b64 s[40:41], -1
	s_waitcnt lgkmcnt(6)
	v_mfma_f32_16x16x32_bf16 v[4:7], v[178:181], v[130:133], v[190:193]
	s_waitcnt lgkmcnt(5)
	v_mfma_f32_16x16x32_bf16 v[0:3], v[186:189], v[134:137], v[0:3]
	s_waitcnt lgkmcnt(4)
	v_mfma_f32_16x16x32_bf16 v[4:7], v[174:177], v[134:137], v[4:7]
	s_nop 5
	v_exp_f32_e32 v0, v0
	v_exp_f32_e32 v1, v1
	v_exp_f32_e32 v2, v2
	v_exp_f32_e32 v3, v3
	v_exp_f32_e32 v4, v4
	v_exp_f32_e32 v5, v5
	v_exp_f32_e32 v6, v6
	v_exp_f32_e32 v7, v7
	s_cbranch_vccz .LBB0_839

.LBB0_840:
	s_mov_b64 s[50:51], s[86:87]
	s_mov_b64 s[48:49], s[88:89]
	s_mov_b64 s[46:47], s[90:91]
	s_mov_b64 s[42:43], s[92:93]
	s_or_b64 s[2:3], s[48:49], s[50:51]
	s_or_b64 s[2:3], s[2:3], s[46:47]
	s_or_b64 s[2:3], s[2:3], s[42:43]
	s_cmp_eq_u64 s[2:3], 0
	s_cbranch_scc1 .LBB0_754
	ds_read_b128 v[182:185], v246 offset:24576
	ds_read_b128 v[178:181], v246 offset:26624
	ds_read_b128 v[186:189], v247 offset:24576
	ds_read_b128 v[174:177], v247 offset:26624
	ds_read_b128 v[158:161], v244 offset:28672
	ds_read_b128 v[162:165], v244 offset:29696
	ds_read_b128 v[166:169], v244 offset:30720
	ds_read_b128 v[170:173], v244 offset:31744
	s_add_i32 s2, s28, 0xffffff5f
	s_cmp_le_i32 s2, s26
	s_cselect_b64 s[2:3], -1, 0
	v_cndmask_b32_e64 v0, 0, 1, s[2:3]
	s_cmp_eq_u64 s[50:51], 0
	v_cmp_ne_u32_e64 s[44:45], 1, v0
	s_cbranch_scc1 .LBB0_847
	v_cndmask_b32_e64 v190, v194, 0, s[50:51]
	v_cndmask_b32_e64 v191, v194, 0, s[50:51]
	v_cndmask_b32_e64 v192, v194, 0, s[50:51]
	v_cndmask_b32_e64 v193, v194, 0, s[50:51]
	s_nop 0
	s_waitcnt lgkmcnt(7)
	v_mfma_f32_16x16x32_bf16 v[0:3], v[182:185], v[104:107], v[190:193]
	s_and_b64 vcc, exec, s[44:45]
	s_mov_b64 s[40:41], -1
	s_waitcnt lgkmcnt(6)
	v_mfma_f32_16x16x32_bf16 v[4:7], v[178:181], v[104:107], v[190:193]
	s_waitcnt lgkmcnt(5)
	v_mfma_f32_16x16x32_bf16 v[0:3], v[186:189], v[108:111], v[0:3]
	s_waitcnt lgkmcnt(4)
	v_mfma_f32_16x16x32_bf16 v[4:7], v[174:177], v[108:111], v[4:7]
	s_nop 5
	v_exp_f32_e32 v0, v0
	v_exp_f32_e32 v1, v1
	v_exp_f32_e32 v2, v2
	v_exp_f32_e32 v3, v3
	v_exp_f32_e32 v4, v4
	v_exp_f32_e32 v5, v5
	v_exp_f32_e32 v6, v6
	v_exp_f32_e32 v7, v7
	s_cbranch_vccz .LBB0_846

.Lsel_have_words2:
	v_and_b32_e32 v0, s70, v250
	v_cmp_ne_u32_e64 s[50:51], 0, v0
	v_and_b32_e32 v0, s70, v251
	v_cmp_ne_u32_e64 s[48:49], 0, v0
	v_and_b32_e32 v0, s70, v249
	v_cmp_ne_u32_e64 s[46:47], 0, v0
	v_and_b32_e32 v0, s70, v248
	v_cmp_ne_u32_e64 s[42:43], 0, v0
	s_mov_b64 s[86:87], s[50:51]
	s_mov_b64 s[88:89], s[48:49]
	s_mov_b64 s[90:91], s[46:47]
	s_mov_b64 s[92:93], s[42:43]
	s_or_b64 s[2:3], s[48:49], s[50:51]
	s_or_b64 s[2:3], s[2:3], s[46:47]
	s_or_b64 s[2:3], s[2:3], s[42:43]
	s_cmp_eq_u64 s[2:3], 0
	s_cbranch_scc1 .LB2_785
	ds_read_b128 v[182:185], v246 offset:32768
	ds_read_b128 v[178:181], v246 offset:34816
	ds_read_b128 v[186:189], v247 offset:32768
	ds_read_b128 v[174:177], v247 offset:34816
	ds_read_b128 v[158:161], v244 offset:36864
	ds_read_b128 v[162:165], v244 offset:37888
	ds_read_b128 v[166:169], v244 offset:38912
	ds_read_b128 v[170:173], v244 offset:39936
	s_add_i32 s2, s28, 0xfffffeff
	s_cmp_le_i32 s2, s26
	s_cselect_b64 s[2:3], -1, 0
	v_cndmask_b32_e64 v0, 0, 1, s[2:3]
	s_cmp_eq_u64 s[50:51], 0
	v_cmp_ne_u32_e64 s[44:45], 1, v0
	s_cbranch_scc1 .LB2_767
	v_cndmask_b32_e64 v190, v194, 0, s[50:51]
	v_cndmask_b32_e64 v191, v194, 0, s[50:51]
	v_cndmask_b32_e64 v192, v194, 0, s[50:51]
	v_cndmask_b32_e64 v193, v194, 0, s[50:51]
	s_nop 0
	s_waitcnt lgkmcnt(7)
	v_mfma_f32_16x16x32_bf16 v[0:3], v[182:185], v[104:107], v[190:193]
	s_and_b64 vcc, exec, s[44:45]
	s_mov_b64 s[64:65], -1
	s_waitcnt lgkmcnt(6)
	v_mfma_f32_16x16x32_bf16 v[4:7], v[178:181], v[104:107], v[190:193]
	s_waitcnt lgkmcnt(5)
	v_mfma_f32_16x16x32_bf16 v[0:3], v[186:189], v[108:111], v[0:3]
	s_waitcnt lgkmcnt(4)
	v_mfma_f32_16x16x32_bf16 v[4:7], v[174:177], v[108:111], v[4:7]
	s_nop 5
	v_exp_f32_e32 v0, v0
	v_exp_f32_e32 v1, v1
	v_exp_f32_e32 v2, v2
	v_exp_f32_e32 v3, v3
	v_exp_f32_e32 v4, v4
	v_exp_f32_e32 v5, v5
	v_exp_f32_e32 v6, v6
	v_exp_f32_e32 v7, v7
	s_cbranch_vccz .LB2_766

.LB2_785:
	s_mov_b64 s[50:51], s[86:87]
	s_mov_b64 s[48:49], s[88:89]
	s_mov_b64 s[46:47], s[90:91]
	s_mov_b64 s[42:43], s[92:93]
	s_or_b64 s[2:3], s[48:49], s[50:51]
	s_or_b64 s[2:3], s[2:3], s[46:47]
	s_or_b64 s[2:3], s[2:3], s[42:43]
	s_cmp_eq_u64 s[2:3], 0
	s_cbranch_scc1 .LB2_810
	ds_read_b128 v[182:185], v246 offset:40960
	ds_read_b128 v[178:181], v246 offset:43008
	ds_read_b128 v[186:189], v247 offset:40960
	ds_read_b128 v[174:177], v247 offset:43008
	ds_read_b128 v[158:161], v244 offset:45056
	ds_read_b128 v[162:165], v244 offset:46080
	ds_read_b128 v[166:169], v244 offset:47104
	ds_read_b128 v[170:173], v244 offset:48128
	s_add_i32 s2, s28, 0xffffff1f
	s_cmp_le_i32 s2, s26
	s_cselect_b64 s[2:3], -1, 0
	v_cndmask_b32_e64 v0, 0, 1, s[2:3]
	s_cmp_eq_u64 s[50:51], 0
	v_cmp_ne_u32_e64 s[44:45], 1, v0
	s_cbranch_scc1 .LB2_792
	v_cndmask_b32_e64 v190, v194, 0, s[50:51]
	v_cndmask_b32_e64 v191, v194, 0, s[50:51]
	v_cndmask_b32_e64 v192, v194, 0, s[50:51]
	v_cndmask_b32_e64 v193, v194, 0, s[50:51]
	s_nop 0
	s_waitcnt lgkmcnt(7)
	v_mfma_f32_16x16x32_bf16 v[0:3], v[182:185], v[104:107], v[190:193]
	s_and_b64 vcc, exec, s[44:45]
	s_mov_b64 s[64:65], -1
	s_waitcnt lgkmcnt(6)
	v_mfma_f32_16x16x32_bf16 v[4:7], v[178:181], v[104:107], v[190:193]
	s_waitcnt lgkmcnt(5)
	v_mfma_f32_16x16x32_bf16 v[0:3], v[186:189], v[108:111], v[0:3]
	s_waitcnt lgkmcnt(4)
	v_mfma_f32_16x16x32_bf16 v[4:7], v[174:177], v[108:111], v[4:7]
	s_nop 5
	v_exp_f32_e32 v0, v0
	v_exp_f32_e32 v1, v1
	v_exp_f32_e32 v2, v2
	v_exp_f32_e32 v3, v3
	v_exp_f32_e32 v4, v4
	v_exp_f32_e32 v5, v5
	v_exp_f32_e32 v6, v6
	v_exp_f32_e32 v7, v7
	s_cbranch_vccz .LB2_791

.LB2_815:
	s_add_i32 s2, s27, -3
	s_lshl_b32 s64, 1, s2
	v_and_b32_e32 v0, s64, v250
	v_cmp_ne_u32_e64 s[50:51], 0, v0
	v_and_b32_e32 v0, s64, v251
	v_cmp_ne_u32_e64 s[48:49], 0, v0
	v_and_b32_e32 v0, s64, v249
	v_cmp_ne_u32_e64 s[46:47], 0, v0
	v_and_b32_e32 v0, s64, v248
	v_cmp_ne_u32_e64 s[42:43], 0, v0
	s_mov_b64 s[86:87], s[50:51]
	s_mov_b64 s[88:89], s[48:49]
	s_mov_b64 s[90:91], s[46:47]
	s_mov_b64 s[92:93], s[42:43]
	s_or_b64 s[2:3], s[48:49], s[50:51]
	s_or_b64 s[2:3], s[2:3], s[46:47]
	s_or_b64 s[2:3], s[2:3], s[42:43]
	s_cmp_eq_u64 s[2:3], 0
	s_cbranch_scc1 .LB2_840
	ds_read_b128 v[182:185], v246 offset:49152
	ds_read_b128 v[178:181], v246 offset:51200
	ds_read_b128 v[186:189], v247 offset:49152
	ds_read_b128 v[174:177], v247 offset:51200
	ds_read_b128 v[158:161], v244 offset:53248
	ds_read_b128 v[162:165], v244 offset:54272
	ds_read_b128 v[166:169], v244 offset:55296
	ds_read_b128 v[170:173], v244 offset:56320
	s_add_i32 s2, s28, 0xffffff3f
	s_cmp_le_i32 s2, s26
	s_cselect_b64 s[2:3], -1, 0
	v_cndmask_b32_e64 v0, 0, 1, s[2:3]
	s_cmp_eq_u64 s[50:51], 0
	v_cmp_ne_u32_e64 s[44:45], 1, v0
	s_cbranch_scc1 .LB2_822
	v_cndmask_b32_e64 v190, v194, 0, s[50:51]
	v_cndmask_b32_e64 v191, v194, 0, s[50:51]
	v_cndmask_b32_e64 v192, v194, 0, s[50:51]
	v_cndmask_b32_e64 v193, v194, 0, s[50:51]
	s_nop 0
	s_waitcnt lgkmcnt(7)
	v_mfma_f32_16x16x32_bf16 v[0:3], v[182:185], v[104:107], v[190:193]
	s_and_b64 vcc, exec, s[44:45]
	s_mov_b64 s[40:41], -1
	s_waitcnt lgkmcnt(6)
	v_mfma_f32_16x16x32_bf16 v[4:7], v[178:181], v[104:107], v[190:193]
	s_waitcnt lgkmcnt(5)
	v_mfma_f32_16x16x32_bf16 v[0:3], v[186:189], v[108:111], v[0:3]
	s_waitcnt lgkmcnt(4)
	v_mfma_f32_16x16x32_bf16 v[4:7], v[174:177], v[108:111], v[4:7]
	s_nop 5
	v_exp_f32_e32 v0, v0
	v_exp_f32_e32 v1, v1
	v_exp_f32_e32 v2, v2
	v_exp_f32_e32 v3, v3
	v_exp_f32_e32 v4, v4
	v_exp_f32_e32 v5, v5
	v_exp_f32_e32 v6, v6
	v_exp_f32_e32 v7, v7
	s_cbranch_vccz .LB2_821

.LB2_840:
	s_mov_b64 s[50:51], s[86:87]
	s_mov_b64 s[48:49], s[88:89]
	s_mov_b64 s[46:47], s[90:91]
	s_mov_b64 s[42:43], s[92:93]
	s_or_b64 s[2:3], s[48:49], s[50:51]
	s_or_b64 s[2:3], s[2:3], s[46:47]
	s_or_b64 s[2:3], s[2:3], s[42:43]
	s_cmp_eq_u64 s[2:3], 0
	s_cbranch_scc1 .LB2_754
	ds_read_b128 v[182:185], v246 offset:57344
	ds_read_b128 v[178:181], v246 offset:59392
	ds_read_b128 v[186:189], v247 offset:57344
	ds_read_b128 v[174:177], v247 offset:59392
	ds_read_b128 v[158:161], v244 offset:61440
	ds_read_b128 v[162:165], v244 offset:62464
	ds_read_b128 v[166:169], v244 offset:63488
	ds_read_b128 v[170:173], v244 offset:64512
	s_add_i32 s2, s28, 0xffffff5f
	s_cmp_le_i32 s2, s26
	s_cselect_b64 s[2:3], -1, 0
	v_cndmask_b32_e64 v0, 0, 1, s[2:3]
	s_cmp_eq_u64 s[50:51], 0
	v_cmp_ne_u32_e64 s[44:45], 1, v0
	s_cbranch_scc1 .LB2_847
	v_cndmask_b32_e64 v190, v194, 0, s[50:51]
	v_cndmask_b32_e64 v191, v194, 0, s[50:51]
	v_cndmask_b32_e64 v192, v194, 0, s[50:51]
	v_cndmask_b32_e64 v193, v194, 0, s[50:51]
	s_nop 0
	s_waitcnt lgkmcnt(7)
	v_mfma_f32_16x16x32_bf16 v[0:3], v[182:185], v[104:107], v[190:193]
	s_and_b64 vcc, exec, s[44:45]
	s_mov_b64 s[40:41], -1
	s_waitcnt lgkmcnt(6)
	v_mfma_f32_16x16x32_bf16 v[4:7], v[178:181], v[104:107], v[190:193]
	s_waitcnt lgkmcnt(5)
	v_mfma_f32_16x16x32_bf16 v[0:3], v[186:189], v[108:111], v[0:3]
	s_waitcnt lgkmcnt(4)
	v_mfma_f32_16x16x32_bf16 v[4:7], v[174:177], v[108:111], v[4:7]
	s_nop 5
	v_exp_f32_e32 v0, v0
	v_exp_f32_e32 v1, v1
	v_exp_f32_e32 v2, v2
	v_exp_f32_e32 v3, v3
	v_exp_f32_e32 v4, v4
	v_exp_f32_e32 v5, v5
	v_exp_f32_e32 v6, v6
	v_exp_f32_e32 v7, v7
	s_cbranch_vccz .LB2_846

.LB2_859:
	s_cmp_eq_u64 s[42:43], 0
	s_cbranch_scc1 .LB2_754
	v_cndmask_b32_e64 v190, v194, 0, s[42:43]
	v_cndmask_b32_e64 v191, v194, 0, s[42:43]
	v_cndmask_b32_e64 v192, v194, 0, s[42:43]
	v_cndmask_b32_e64 v193, v194, 0, s[42:43]
	s_nop 0
	s_waitcnt lgkmcnt(7)
	v_mfma_f32_16x16x32_bf16 v[0:3], v[182:185], v[130:133], v[190:193]
	s_and_b64 vcc, exec, s[44:45]
	s_mov_b64 s[40:41], -1
	s_waitcnt lgkmcnt(6)
	v_mfma_f32_16x16x32_bf16 v[4:7], v[178:181], v[130:133], v[190:193]
	s_waitcnt lgkmcnt(5)
	v_mfma_f32_16x16x32_bf16 v[0:3], v[186:189], v[134:137], v[0:3]
	s_waitcnt lgkmcnt(4)
	v_mfma_f32_16x16x32_bf16 v[4:7], v[174:177], v[134:137], v[4:7]
	s_nop 5
	v_exp_f32_e32 v0, v0
	v_exp_f32_e32 v1, v1
	v_exp_f32_e32 v2, v2
	v_exp_f32_e32 v3, v3
	v_exp_f32_e32 v4, v4
	v_exp_f32_e32 v5, v5
	v_exp_f32_e32 v6, v6
	v_exp_f32_e32 v7, v7
	s_cbranch_vccnz .LB2_862
	s_mov_b64 s[40:41], 0
